# tabB_lat hand loop: one ds_read_b64 per (cos,sin) pair, both output rows per step
# baseline (speedup 1.0000x reference)
.Lwt_fast:
	v_and_b32_e32 v200, 63, v176
	v_lshrrev_b32_e32 v201, 6, v176
	v_lshl_add_u32 v200, v201, 9, v200
	v_add_u32_e32 v202, 0, v200
	v_lshlrev_b32_e32 v210, 1, v202
	v_add_u32_e32 v203, 64, v200
	v_lshlrev_b32_e32 v211, 1, v203
	v_add_u32_e32 v204, 128, v200
	v_lshlrev_b32_e32 v212, 1, v204
	v_add_u32_e32 v205, 192, v200
	v_lshlrev_b32_e32 v213, 1, v205
	v_add_u32_e32 v206, 256, v200
	v_lshlrev_b32_e32 v214, 1, v206
	v_add_u32_e32 v207, 320, v200
	v_lshlrev_b32_e32 v215, 1, v207
	v_add_u32_e32 v208, 384, v200
	v_lshlrev_b32_e32 v216, 1, v208
	v_add_u32_e32 v209, 448, v200
	v_lshlrev_b32_e32 v217, 1, v209
	v_readlane_b32 s4, v252, 6
	v_readlane_b32 s5, v252, 7
	s_brev_b32 s6, 1
	s_lshl_b32 s0, s94, 2
.Ltb_loop:
	s_mov_b32 s1, s0
	s_lshl_b32 s7, s0, 13
	s_add_u32 s8, s4, s7
	s_addc_u32 s9, s5, 0
	s_add_u32 s10, s8, 0x1000
	s_addc_u32 s11, s9, 0
	s_and_b32 s3, s1, 7
	s_cmp_lg_u32 s3, 0
	s_cbranch_scc1 .Ltb_n8
	s_and_b32 s3, s1, 15
	s_cmp_lg_u32 s3, 0
	s_cbranch_scc1 .Ltb_n4
	s_and_b32 s3, s1, 31
	s_cmp_lg_u32 s3, 0
	s_cbranch_scc1 .Ltb_n2
	v_mul_u32_u24_e32 v218, s1, v202
	v_and_b32_e32 v218, 0x7ff, v218
	v_lshlrev_b32_e32 v218, 3, v218
	ds_read_b64 v[226:227], v218
	s_waitcnt lgkmcnt(0)
	v_xor_b32_e32 v227, s6, v227
	s_nop 1
	v_mov_b32_dpp v242, v226 quad_perm:[1,0,3,2] row_mask:0xf bank_mask:0xf
	v_cvt_pk_bf16_f32 v226, v226, v242
	s_nop 1
	v_mov_b32_dpp v242, v227 quad_perm:[1,0,3,2] row_mask:0xf bank_mask:0xf
	v_cvt_pk_bf16_f32 v227, v227, v242
	s_mov_b32 exec_lo, 0x55555555
	s_mov_b32 exec_hi, 0x55555555
	global_store_dword v210, v226, s[8:9]
	global_store_dword v211, v226, s[8:9]
	global_store_dword v212, v226, s[8:9]
	global_store_dword v213, v226, s[8:9]
	global_store_dword v214, v226, s[8:9]
	global_store_dword v215, v226, s[8:9]
	global_store_dword v216, v226, s[8:9]
	global_store_dword v217, v226, s[8:9]
	global_store_dword v210, v227, s[10:11]
	global_store_dword v211, v227, s[10:11]
	global_store_dword v212, v227, s[10:11]
	global_store_dword v213, v227, s[10:11]
	global_store_dword v214, v227, s[10:11]
	global_store_dword v215, v227, s[10:11]
	global_store_dword v216, v227, s[10:11]
	global_store_dword v217, v227, s[10:11]
	s_mov_b64 exec, -1
	s_branch .Ltb_next
.Ltb_n2:
	v_mul_u32_u24_e32 v218, s1, v202
	v_and_b32_e32 v218, 0x7ff, v218
	v_lshlrev_b32_e32 v218, 3, v218
	ds_read_b64 v[226:227], v218
	v_mul_u32_u24_e32 v219, s1, v203
	v_and_b32_e32 v219, 0x7ff, v219
	v_lshlrev_b32_e32 v219, 3, v219
	ds_read_b64 v[228:229], v219
	s_waitcnt lgkmcnt(0)
	v_xor_b32_e32 v227, s6, v227
	v_xor_b32_e32 v229, s6, v229
	s_nop 1
	v_mov_b32_dpp v242, v226 quad_perm:[1,0,3,2] row_mask:0xf bank_mask:0xf
	v_mov_b32_dpp v243, v228 quad_perm:[1,0,3,2] row_mask:0xf bank_mask:0xf
	v_cvt_pk_bf16_f32 v226, v226, v242
	v_cvt_pk_bf16_f32 v228, v228, v243
	s_nop 1
	v_mov_b32_dpp v242, v227 quad_perm:[1,0,3,2] row_mask:0xf bank_mask:0xf
	v_mov_b32_dpp v243, v229 quad_perm:[1,0,3,2] row_mask:0xf bank_mask:0xf
	v_cvt_pk_bf16_f32 v227, v227, v242
	v_cvt_pk_bf16_f32 v229, v229, v243
	s_mov_b32 exec_lo, 0x55555555
	s_mov_b32 exec_hi, 0x55555555
	global_store_dword v210, v226, s[8:9]
	global_store_dword v211, v228, s[8:9]
	global_store_dword v212, v226, s[8:9]
	global_store_dword v213, v228, s[8:9]
	global_store_dword v214, v226, s[8:9]
	global_store_dword v215, v228, s[8:9]
	global_store_dword v216, v226, s[8:9]
	global_store_dword v217, v228, s[8:9]
	global_store_dword v210, v227, s[10:11]
	global_store_dword v211, v229, s[10:11]
	global_store_dword v212, v227, s[10:11]
	global_store_dword v213, v229, s[10:11]
	global_store_dword v214, v227, s[10:11]
	global_store_dword v215, v229, s[10:11]
	global_store_dword v216, v227, s[10:11]
	global_store_dword v217, v229, s[10:11]
	s_mov_b64 exec, -1
	s_branch .Ltb_next
.Ltb_n4:
	v_mul_u32_u24_e32 v218, s1, v202
	v_and_b32_e32 v218, 0x7ff, v218
	v_lshlrev_b32_e32 v218, 3, v218
	ds_read_b64 v[226:227], v218
	v_mul_u32_u24_e32 v219, s1, v203
	v_and_b32_e32 v219, 0x7ff, v219
	v_lshlrev_b32_e32 v219, 3, v219
	ds_read_b64 v[228:229], v219
	v_mul_u32_u24_e32 v220, s1, v204
	v_and_b32_e32 v220, 0x7ff, v220
	v_lshlrev_b32_e32 v220, 3, v220
	ds_read_b64 v[230:231], v220
	v_mul_u32_u24_e32 v221, s1, v205
	v_and_b32_e32 v221, 0x7ff, v221
	v_lshlrev_b32_e32 v221, 3, v221
	ds_read_b64 v[232:233], v221
	s_waitcnt lgkmcnt(0)
	v_xor_b32_e32 v227, s6, v227
	v_xor_b32_e32 v229, s6, v229
	v_xor_b32_e32 v231, s6, v231
	v_xor_b32_e32 v233, s6, v233
	s_nop 1
	v_mov_b32_dpp v242, v226 quad_perm:[1,0,3,2] row_mask:0xf bank_mask:0xf
	v_mov_b32_dpp v243, v228 quad_perm:[1,0,3,2] row_mask:0xf bank_mask:0xf
	v_mov_b32_dpp v244, v230 quad_perm:[1,0,3,2] row_mask:0xf bank_mask:0xf
	v_mov_b32_dpp v245, v232 quad_perm:[1,0,3,2] row_mask:0xf bank_mask:0xf
	v_cvt_pk_bf16_f32 v226, v226, v242
	v_cvt_pk_bf16_f32 v228, v228, v243
	v_cvt_pk_bf16_f32 v230, v230, v244
	v_cvt_pk_bf16_f32 v232, v232, v245
	s_nop 1
	v_mov_b32_dpp v242, v227 quad_perm:[1,0,3,2] row_mask:0xf bank_mask:0xf
	v_mov_b32_dpp v243, v229 quad_perm:[1,0,3,2] row_mask:0xf bank_mask:0xf
	v_mov_b32_dpp v244, v231 quad_perm:[1,0,3,2] row_mask:0xf bank_mask:0xf
	v_mov_b32_dpp v245, v233 quad_perm:[1,0,3,2] row_mask:0xf bank_mask:0xf
	v_cvt_pk_bf16_f32 v227, v227, v242
	v_cvt_pk_bf16_f32 v229, v229, v243
	v_cvt_pk_bf16_f32 v231, v231, v244
	v_cvt_pk_bf16_f32 v233, v233, v245
	s_mov_b32 exec_lo, 0x55555555
	s_mov_b32 exec_hi, 0x55555555
	global_store_dword v210, v226, s[8:9]
	global_store_dword v211, v228, s[8:9]
	global_store_dword v212, v230, s[8:9]
	global_store_dword v213, v232, s[8:9]
	global_store_dword v214, v226, s[8:9]
	global_store_dword v215, v228, s[8:9]
	global_store_dword v216, v230, s[8:9]
	global_store_dword v217, v232, s[8:9]
	global_store_dword v210, v227, s[10:11]
	global_store_dword v211, v229, s[10:11]
	global_store_dword v212, v231, s[10:11]
	global_store_dword v213, v233, s[10:11]
	global_store_dword v214, v227, s[10:11]
	global_store_dword v215, v229, s[10:11]
	global_store_dword v216, v231, s[10:11]
	global_store_dword v217, v233, s[10:11]
	s_mov_b64 exec, -1
	s_branch .Ltb_next
.Ltb_n8:
	v_mul_u32_u24_e32 v218, s1, v202
	v_and_b32_e32 v218, 0x7ff, v218
	v_lshlrev_b32_e32 v218, 3, v218
	ds_read_b64 v[226:227], v218
	v_mul_u32_u24_e32 v219, s1, v203
	v_and_b32_e32 v219, 0x7ff, v219
	v_lshlrev_b32_e32 v219, 3, v219
	ds_read_b64 v[228:229], v219
	v_mul_u32_u24_e32 v220, s1, v204
	v_and_b32_e32 v220, 0x7ff, v220
	v_lshlrev_b32_e32 v220, 3, v220
	ds_read_b64 v[230:231], v220
	v_mul_u32_u24_e32 v221, s1, v205
	v_and_b32_e32 v221, 0x7ff, v221
	v_lshlrev_b32_e32 v221, 3, v221
	ds_read_b64 v[232:233], v221
	v_mul_u32_u24_e32 v222, s1, v206
	v_and_b32_e32 v222, 0x7ff, v222
	v_lshlrev_b32_e32 v222, 3, v222
	ds_read_b64 v[234:235], v222
	v_mul_u32_u24_e32 v223, s1, v207
	v_and_b32_e32 v223, 0x7ff, v223
	v_lshlrev_b32_e32 v223, 3, v223
	ds_read_b64 v[236:237], v223
	v_mul_u32_u24_e32 v224, s1, v208
	v_and_b32_e32 v224, 0x7ff, v224
	v_lshlrev_b32_e32 v224, 3, v224
	ds_read_b64 v[238:239], v224
	v_mul_u32_u24_e32 v225, s1, v209
	v_and_b32_e32 v225, 0x7ff, v225
	v_lshlrev_b32_e32 v225, 3, v225
	ds_read_b64 v[240:241], v225
	s_waitcnt lgkmcnt(0)
	v_xor_b32_e32 v227, s6, v227
	v_xor_b32_e32 v229, s6, v229
	v_xor_b32_e32 v231, s6, v231
	v_xor_b32_e32 v233, s6, v233
	v_xor_b32_e32 v235, s6, v235
	v_xor_b32_e32 v237, s6, v237
	v_xor_b32_e32 v239, s6, v239
	v_xor_b32_e32 v241, s6, v241
	s_nop 1
	v_mov_b32_dpp v242, v226 quad_perm:[1,0,3,2] row_mask:0xf bank_mask:0xf
	v_mov_b32_dpp v243, v228 quad_perm:[1,0,3,2] row_mask:0xf bank_mask:0xf
	v_mov_b32_dpp v244, v230 quad_perm:[1,0,3,2] row_mask:0xf bank_mask:0xf
	v_mov_b32_dpp v245, v232 quad_perm:[1,0,3,2] row_mask:0xf bank_mask:0xf
	v_mov_b32_dpp v246, v234 quad_perm:[1,0,3,2] row_mask:0xf bank_mask:0xf
	v_mov_b32_dpp v247, v236 quad_perm:[1,0,3,2] row_mask:0xf bank_mask:0xf
	v_mov_b32_dpp v248, v238 quad_perm:[1,0,3,2] row_mask:0xf bank_mask:0xf
	v_mov_b32_dpp v249, v240 quad_perm:[1,0,3,2] row_mask:0xf bank_mask:0xf
	v_cvt_pk_bf16_f32 v226, v226, v242
	v_cvt_pk_bf16_f32 v228, v228, v243
	v_cvt_pk_bf16_f32 v230, v230, v244
	v_cvt_pk_bf16_f32 v232, v232, v245
	v_cvt_pk_bf16_f32 v234, v234, v246
	v_cvt_pk_bf16_f32 v236, v236, v247
	v_cvt_pk_bf16_f32 v238, v238, v248
	v_cvt_pk_bf16_f32 v240, v240, v249
	s_nop 1
	v_mov_b32_dpp v242, v227 quad_perm:[1,0,3,2] row_mask:0xf bank_mask:0xf
	v_mov_b32_dpp v243, v229 quad_perm:[1,0,3,2] row_mask:0xf bank_mask:0xf
	v_mov_b32_dpp v244, v231 quad_perm:[1,0,3,2] row_mask:0xf bank_mask:0xf
	v_mov_b32_dpp v245, v233 quad_perm:[1,0,3,2] row_mask:0xf bank_mask:0xf
	v_mov_b32_dpp v246, v235 quad_perm:[1,0,3,2] row_mask:0xf bank_mask:0xf
	v_mov_b32_dpp v247, v237 quad_perm:[1,0,3,2] row_mask:0xf bank_mask:0xf
	v_mov_b32_dpp v248, v239 quad_perm:[1,0,3,2] row_mask:0xf bank_mask:0xf
	v_mov_b32_dpp v249, v241 quad_perm:[1,0,3,2] row_mask:0xf bank_mask:0xf
	v_cvt_pk_bf16_f32 v227, v227, v242
	v_cvt_pk_bf16_f32 v229, v229, v243
	v_cvt_pk_bf16_f32 v231, v231, v244
	v_cvt_pk_bf16_f32 v233, v233, v245
	v_cvt_pk_bf16_f32 v235, v235, v246
	v_cvt_pk_bf16_f32 v237, v237, v247
	v_cvt_pk_bf16_f32 v239, v239, v248
	v_cvt_pk_bf16_f32 v241, v241, v249
	s_mov_b32 exec_lo, 0x55555555
	s_mov_b32 exec_hi, 0x55555555
	global_store_dword v210, v226, s[8:9]
	global_store_dword v211, v228, s[8:9]
	global_store_dword v212, v230, s[8:9]
	global_store_dword v213, v232, s[8:9]
	global_store_dword v214, v234, s[8:9]
	global_store_dword v215, v236, s[8:9]
	global_store_dword v216, v238, s[8:9]
	global_store_dword v217, v240, s[8:9]
	global_store_dword v210, v227, s[10:11]
	global_store_dword v211, v229, s[10:11]
	global_store_dword v212, v231, s[10:11]
	global_store_dword v213, v233, s[10:11]
	global_store_dword v214, v235, s[10:11]
	global_store_dword v215, v237, s[10:11]
	global_store_dword v216, v239, s[10:11]
	global_store_dword v217, v241, s[10:11]
	s_mov_b64 exec, -1
.Ltb_next:
	s_add_i32 s0, s0, 1
	s_and_b32 s1, s0, 3
	s_cmp_lg_u32 s1, 0
	s_cbranch_scc1 .Ltb_loop
	s_barrier
	v_and_b32_e32 v120, 63, v176
	v_lshrrev_b32_e32 v121, 6, v176
	v_lshlrev_b32_e32 v122, 2, v120
	v_mul_u32_u24_e32 v123, 65, v120
	v_add_lshl_u32 v123, v123, v121, 2
	v_lshrrev_b32_e32 v129, 2, v176
	v_mul_u32_u24_e32 v124, 65, v129
	v_lshlrev_b32_e32 v125, 11, v129
	v_and_b32_e32 v129, 3, v176
	v_lshl_add_u32 v124, v129, 4, v124
	v_lshlrev_b32_e32 v124, 2, v124
	v_lshl_add_u32 v125, v129, 5, v125
	v_add_u32_e32 v127, 0x4100, v123
	v_add_u32_e32 v128, 0x4100, v124
	s_mov_b32 s1, 0
	s_mov_b32 s0, s94
	s_cmpk_lt_u32 s94, 0x150
	s_cbranch_scc1 .Lwt_start
	s_sub_i32 s0, s94, 0x150
	s_mul_i32 s0, s0, 6
	s_addk_i32 s0, 0x150
